# SwiGLU GEMM epilogue: shift@W operand loads issued before the next tile's LDS-DMA prologue burst, counted vmcnt(14) so the DMA stays in flight under the epilogue instead of being drained at its first
# speedup vs baseline: 1.0030x; 1.0030x over previous
; DI unsigned pk2(float a, float b) { f2_t v = {a, b}; bf2_t r = __builtin_convertvector(v, bf2_t); return __builtin_bit_cast(unsigned, r); }
; DI float silu_mul(float a, float b) { return a * b * __builtin_amdgcn_rcpf(1.f + __builtin_amdgcn_exp2f(a * -1.4426950408889634f)); }
;   DI void operator()(f32x4 (&acc)[2][2][4][2], int brow, int bcol, int wr, int wc, int fr, int fq, const int nai) const {
;     const int bi = brow < M_LAT ? (brow >> 11) : 8;
;     const float* swr = sw + bi * SW_LD + bcol + wc * 32 + fq * 4;
;     const float4 sa0 = ld4(swr), sa1 = ld4(swr + 16), sb0 = ld4(swr + 128), sb1 = ld4(swr + 144);
;     u16* ob = act + (size_t)(brow + wr * 64 + fr) * DFF + (bcol >> 1) + wc * 32;
; #pragma unroll
;     for (int ai = 0; ai < 2; ++ai)
;      if (ai < nai)
; #pragma unroll
;       for (int m = 0; m < 4; ++m) {
;         const float r = rl[ai * 128 + wr * 64 + m * 16 + fr];
;         u16* o_ = ob + (size_t)(ai * 128 + m * 16) * DFF;
;         u32x2 p0, p1;
;         {
;           const f32x4 a = acc[ai][0][m][0], b = acc[ai][1][m][0];
;           p0[0] = pk2(silu_mul(a[0] * r + sa0.x, b[0] * r + sb0.x), silu_mul(a[1] * r + sa0.y, b[1] * r + sb0.y));
;           p0[1] = pk2(silu_mul(a[2] * r + sa0.z, b[2] * r + sb0.z), silu_mul(a[3] * r + sa0.w, b[3] * r + sb0.w));
;         }
;         {
;           const f32x4 a = acc[ai][0][m][1], b = acc[ai][1][m][1];
;           p1[0] = pk2(silu_mul(a[0] * r + sa1.x, b[0] * r + sb1.x), silu_mul(a[1] * r + sa1.y, b[1] * r + sb1.y));
;           p1[1] = pk2(silu_mul(a[2] * r + sa1.z, b[2] * r + sb1.z), silu_mul(a[3] * r + sa1.w, b[3] * r + sb1.w));
;         }
;         store_nn16(o_, p0, p1, fq);
;       }
;   }
.LBB0_969:
	s_min_i32 s0, s2, 0x4000
	s_ashr_i32 s0, s0, 11
	s_mul_hi_i32 s1, s0, 0x5800
	s_mulk_i32 s0, 0x5800
	s_add_u32 s3, s16, s0
	s_addc_u32 s4, s17, s1
	s_lshl_b64 s[0:1], s[8:9], 2
	v_lshrrev_b32_e32 v33, 1, v138
	s_add_u32 s0, s3, s0
	v_and_b32_e32 v34, 0x60, v33
	s_addc_u32 s1, s4, s1
	v_lshlrev_b32_e32 v0, 2, v34
	v_lshl_add_u64 v[30:31], s[0:1], 0, v[0:1]
	v_and_b32_e32 v0, 48, v138
	v_and_b32_e32 v32, 15, v138
	v_lshl_add_u64 v[142:143], v[30:31], 0, v[0:1]
	v_ashrrev_i32_e32 v0, 2, v138
	v_and_b32_e32 v35, 0xffffffc0, v0
	v_or_b32_e32 v0, s2, v32
	v_add_u32_e32 v0, v0, v35
	v_mov_b64_e32 v[30:31], s[40:41]
	s_movk_i32 s0, 0x1600
	v_mad_i64_i32 v[30:31], s[0:1], v0, s0, v[30:31]
	s_lshl_b32 s0, s20, 7
	s_ashr_i32 s1, s0, 31
	v_lshl_add_u64 v[30:31], s[0:1], 1, v[30:31]
	v_lshlrev_b32_e32 v0, 1, v34
	v_lshl_add_u64 v[30:31], v[30:31], 0, v[0:1]
	v_and_b32_e32 v0, 16, v138
	v_lshlrev_b32_e32 v0, 1, v0
	v_lshl_add_u64 v[30:31], v[30:31], 0, v[0:1]
	v_and_b32_e32 v0, 16, v33
	v_lshl_add_u64 v[138:139], v[30:31], 0, v[0:1]
	s_add_i32 s0, 0, 0x25040
	v_lshlrev_b32_e32 v0, 2, v35
	v_lshlrev_b32_e32 v30, 2, v32
	v_add3_u32 v144, s0, v0, v30
	ds_read2_b32 v[140:141], v144 offset1:16
	s_mov_b32 s0, 0x16000
	s_waitcnt lgkmcnt(0)
	v_pk_fma_f32 v[42:43], v[42:43], v[140:141], v[160:161] op_sel_hi:[1,0,1]
	s_nop 0
	v_mul_f32_e32 v0, 0xbfb8aa3b, v42
	v_exp_f32_e32 v0, v0
	v_pk_fma_f32 v[46:47], v[46:47], v[140:141], v[164:165] op_sel_hi:[1,0,1]
	v_add_f32_e32 v0, 1.0, v0
	v_rcp_f32_e32 v146, v0
	v_mul_f32_e32 v0, 0xbfb8aa3b, v43
	v_exp_f32_e32 v0, v0
	v_pk_mul_f32 v[46:47], v[42:43], v[46:47]
	v_add_f32_e32 v0, 1.0, v0
	v_rcp_f32_e32 v147, v0
	s_nop 0
	v_pk_mul_f32 v[42:43], v[46:47], v[146:147]
	s_nop 0
	v_cvt_pk_bf16_f32 v146, v42, v43
	v_pk_fma_f32 v[42:43], v[44:45], v[140:141], v[162:163] op_sel_hi:[1,0,1]
	v_pk_fma_f32 v[46:47], v[48:49], v[140:141], v[166:167] op_sel_hi:[1,0,1]
	v_mul_f32_e32 v0, 0xbfb8aa3b, v42
	v_exp_f32_e32 v0, v0
	v_pk_mul_f32 v[46:47], v[42:43], v[46:47]
	v_add_f32_e32 v0, 1.0, v0
	v_rcp_f32_e32 v44, v0
	v_mul_f32_e32 v0, 0xbfb8aa3b, v43
	v_exp_f32_e32 v0, v0
	s_nop 0
	v_add_f32_e32 v0, 1.0, v0
	v_rcp_f32_e32 v45, v0
	s_nop 0
	v_pk_mul_f32 v[42:43], v[46:47], v[44:45]
	s_nop 0
	v_cvt_pk_bf16_f32 v147, v42, v43
	v_pk_fma_f32 v[130:131], v[130:131], v[140:141], v[168:169] op_sel_hi:[1,0,1]
	s_nop 0
	v_mul_f32_e32 v0, 0xbfb8aa3b, v130
	v_exp_f32_e32 v0, v0
	v_pk_fma_f32 v[134:135], v[134:135], v[140:141], v[172:173] op_sel_hi:[1,0,1]
	v_add_f32_e32 v0, 1.0, v0
	v_rcp_f32_e32 v142, v0
	v_mul_f32_e32 v0, 0xbfb8aa3b, v131
	v_exp_f32_e32 v0, v0
	v_pk_mul_f32 v[134:135], v[130:131], v[134:135]
	v_add_f32_e32 v0, 1.0, v0
	v_rcp_f32_e32 v143, v0
	s_nop 0
	v_pk_mul_f32 v[130:131], v[134:135], v[142:143]
	s_nop 0
	v_cvt_pk_bf16_f32 v148, v130, v131
	v_pk_fma_f32 v[130:131], v[132:133], v[140:141], v[170:171] op_sel_hi:[1,0,1]
	v_pk_fma_f32 v[134:135], v[136:137], v[140:141], v[174:175] op_sel_hi:[1,0,1]
	v_mul_f32_e32 v0, 0xbfb8aa3b, v130
	v_exp_f32_e32 v0, v0
	v_pk_mul_f32 v[134:135], v[130:131], v[134:135]
	v_permlane16_swap_b32_e32 v146, v148
	v_add_f32_e32 v0, 1.0, v0
	v_rcp_f32_e32 v132, v0
	v_mul_f32_e32 v0, 0xbfb8aa3b, v131
	v_exp_f32_e32 v0, v0
	s_nop 0
	v_add_f32_e32 v0, 1.0, v0
	v_rcp_f32_e32 v133, v0
	v_mov_b32_e32 v0, v141
	v_pk_fma_f32 v[122:123], v[122:123], v[0:1], v[160:161] op_sel_hi:[1,0,1]
	v_pk_fma_f32 v[126:127], v[126:127], v[0:1], v[164:165] op_sel_hi:[1,0,1]
	v_pk_mul_f32 v[130:131], v[134:135], v[132:133]
	v_pk_mul_f32 v[126:127], v[122:123], v[126:127]
	v_cvt_pk_bf16_f32 v149, v130, v131
	v_mul_f32_e32 v130, 0xbfb8aa3b, v122
	v_mul_f32_e32 v122, 0xbfb8aa3b, v123
	v_exp_f32_e32 v130, v130
	v_exp_f32_e32 v122, v122
	v_pk_fma_f32 v[124:125], v[124:125], v[0:1], v[162:163] op_sel_hi:[1,0,1]
	v_pk_fma_f32 v[128:129], v[128:129], v[0:1], v[166:167] op_sel_hi:[1,0,1]
	v_add_f32_e32 v130, 1.0, v130
	v_add_f32_e32 v122, 1.0, v122
	v_rcp_f32_e32 v130, v130
	v_rcp_f32_e32 v131, v122
	v_pk_mul_f32 v[128:129], v[124:125], v[128:129]
	v_pk_fma_f32 v[114:115], v[114:115], v[0:1], v[168:169] op_sel_hi:[1,0,1]
	v_pk_fma_f32 v[118:119], v[118:119], v[0:1], v[172:173] op_sel_hi:[1,0,1]
	v_pk_mul_f32 v[122:123], v[126:127], v[130:131]
	v_pk_mul_f32 v[118:119], v[114:115], v[118:119]
	v_cvt_pk_bf16_f32 v122, v122, v123
	v_mul_f32_e32 v123, 0xbfb8aa3b, v124
	v_exp_f32_e32 v123, v123
	v_permlane16_swap_b32_e32 v147, v149
	global_store_dwordx4 v[138:139], v[146:149], off
	v_add_f32_e32 v123, 1.0, v123
	v_rcp_f32_e32 v126, v123
	v_mul_f32_e32 v123, 0xbfb8aa3b, v125
	v_exp_f32_e32 v123, v123
	s_nop 0
	v_add_f32_e32 v123, 1.0, v123
	v_rcp_f32_e32 v127, v123
	s_nop 0
	v_pk_mul_f32 v[124:125], v[128:129], v[126:127]
	s_nop 0
	v_cvt_pk_bf16_f32 v123, v124, v125
	v_mul_f32_e32 v124, 0xbfb8aa3b, v114
	v_mul_f32_e32 v114, 0xbfb8aa3b, v115
	v_exp_f32_e32 v124, v124
	v_exp_f32_e32 v114, v114
	v_add_f32_e32 v124, 1.0, v124
	v_add_f32_e32 v114, 1.0, v114
	v_rcp_f32_e32 v124, v124
	v_rcp_f32_e32 v125, v114
	s_nop 0
	v_pk_mul_f32 v[114:115], v[118:119], v[124:125]
	s_nop 0
	v_cvt_pk_bf16_f32 v124, v114, v115
	v_pk_fma_f32 v[114:115], v[116:117], v[0:1], v[170:171] op_sel_hi:[1,0,1]
	v_pk_fma_f32 v[118:119], v[120:121], v[0:1], v[174:175] op_sel_hi:[1,0,1]
	v_mul_f32_e32 v116, 0xbfb8aa3b, v114
	v_mul_f32_e32 v0, 0xbfb8aa3b, v115
	v_exp_f32_e32 v116, v116
	v_exp_f32_e32 v0, v0
	v_pk_mul_f32 v[118:119], v[114:115], v[118:119]
	v_permlane16_swap_b32_e32 v122, v124
	v_add_f32_e32 v116, 1.0, v116
	v_add_f32_e32 v0, 1.0, v0
	v_rcp_f32_e32 v116, v116
	v_rcp_f32_e32 v117, v0
	s_nop 0
	v_pk_mul_f32 v[114:115], v[118:119], v[116:117]
	s_nop 0
	v_cvt_pk_bf16_f32 v125, v114, v115
	v_add_co_u32_e32 v114, vcc, s0, v138
	s_nop 0
	v_permlane16_swap_b32_e32 v123, v125
	v_addc_co_u32_e32 v115, vcc, 0, v139, vcc
	global_store_dwordx4 v[114:115], v[122:125], off
	ds_read2_b32 v[114:115], v144 offset0:32 offset1:48
	s_mov_b32 s0, 0x2c000
	s_waitcnt lgkmcnt(0)
; DI unsigned pk2(float a, float b) { f2_t v = {a, b}; bf2_t r = __builtin_convertvector(v, bf2_t); return __builtin_bit_cast(unsigned, r); }
; DI float silu_mul(float a, float b) { return a * b * __builtin_amdgcn_rcpf(1.f + __builtin_amdgcn_exp2f(a * -1.4426950408889634f)); }
;   DI void operator()(f32x4 (&acc)[2][2][4][2], int brow, int bcol, int wr, int wc, int fr, int fq, const int nai) const {
;     ...
;         const float r = rl[ai * 128 + wr * 64 + m * 16 + fr];
;         u16* o_ = ob + (size_t)(ai * 128 + m * 16) * DFF;
;         u32x2 p0, p1;
;         {
;           const f32x4 a = acc[ai][0][m][0], b = acc[ai][1][m][0];
;           p0[0] = pk2(silu_mul(a[0] * r + sa0.x, b[0] * r + sb0.x), silu_mul(a[1] * r + sa0.y, b[1] * r + sb0.y));
;           p0[1] = pk2(silu_mul(a[2] * r + sa0.z, b[2] * r + sb0.z), silu_mul(a[3] * r + sa0.w, b[3] * r + sb0.w));
;         }
;         {
;           const f32x4 a = acc[ai][0][m][1], b = acc[ai][1][m][1];
;           p1[0] = pk2(silu_mul(a[0] * r + sa1.x, b[0] * r + sb1.x), silu_mul(a[1] * r + sa1.y, b[1] * r + sb1.y));
;           p1[1] = pk2(silu_mul(a[2] * r + sa1.z, b[2] * r + sb1.z), silu_mul(a[3] * r + sa1.w, b[3] * r + sb1.w));
;         }
;         store_nn16(o_, p0, p1, fq);
;       }
	v_pk_fma_f32 v[106:107], v[106:107], v[114:115], v[160:161] op_sel_hi:[1,0,1]
	s_nop 0
	v_mul_f32_e32 v0, 0xbfb8aa3b, v106
	v_exp_f32_e32 v0, v0
	v_pk_fma_f32 v[108:109], v[108:109], v[114:115], v[162:163] op_sel_hi:[1,0,1]
	v_pk_fma_f32 v[110:111], v[110:111], v[114:115], v[164:165] op_sel_hi:[1,0,1]
	v_pk_fma_f32 v[98:99], v[98:99], v[114:115], v[168:169] op_sel_hi:[1,0,1]
	v_add_f32_e32 v0, 1.0, v0
	v_rcp_f32_e32 v116, v0
	v_mul_f32_e32 v0, 0xbfb8aa3b, v107
	v_exp_f32_e32 v0, v0
	v_pk_mul_f32 v[110:111], v[106:107], v[110:111]
	v_pk_fma_f32 v[112:113], v[112:113], v[114:115], v[166:167] op_sel_hi:[1,0,1]
	v_pk_fma_f32 v[102:103], v[102:103], v[114:115], v[172:173] op_sel_hi:[1,0,1]
	v_add_f32_e32 v0, 1.0, v0
	v_rcp_f32_e32 v117, v0
	v_mul_f32_e32 v0, 0xbfb8aa3b, v108
	v_exp_f32_e32 v0, v0
	v_pk_mul_f32 v[112:113], v[108:109], v[112:113]
	v_pk_mul_f32 v[106:107], v[110:111], v[116:117]
	v_pk_mul_f32 v[102:103], v[98:99], v[102:103]
	v_add_f32_e32 v0, 1.0, v0
	v_rcp_f32_e32 v110, v0
	v_mul_f32_e32 v0, 0xbfb8aa3b, v109
	v_exp_f32_e32 v0, v0
	v_cvt_pk_bf16_f32 v106, v106, v107
	v_add_f32_e32 v0, 1.0, v0
	v_rcp_f32_e32 v111, v0
	v_mul_f32_e32 v0, 0xbfb8aa3b, v98
	v_exp_f32_e32 v0, v0
	v_pk_mul_f32 v[108:109], v[112:113], v[110:111]
	s_nop 0
	v_cvt_pk_bf16_f32 v107, v108, v109
	v_add_f32_e32 v0, 1.0, v0
	v_rcp_f32_e32 v108, v0
	v_mul_f32_e32 v0, 0xbfb8aa3b, v99
	v_exp_f32_e32 v0, v0
	s_nop 0
	v_add_f32_e32 v0, 1.0, v0
	v_rcp_f32_e32 v109, v0
	s_nop 0
	v_pk_mul_f32 v[98:99], v[102:103], v[108:109]
	s_nop 0
	v_cvt_pk_bf16_f32 v108, v98, v99
	v_pk_fma_f32 v[98:99], v[100:101], v[114:115], v[170:171] op_sel_hi:[1,0,1]
	v_pk_fma_f32 v[102:103], v[104:105], v[114:115], v[174:175] op_sel_hi:[1,0,1]
	v_mul_f32_e32 v0, 0xbfb8aa3b, v98
	v_exp_f32_e32 v0, v0
	v_pk_mul_f32 v[102:103], v[98:99], v[102:103]
	v_permlane16_swap_b32_e32 v106, v108
	v_add_f32_e32 v0, 1.0, v0
	v_rcp_f32_e32 v100, v0
	v_mul_f32_e32 v0, 0xbfb8aa3b, v99
	v_exp_f32_e32 v0, v0
	s_nop 0
	v_add_f32_e32 v0, 1.0, v0
	v_rcp_f32_e32 v101, v0
	v_mov_b32_e32 v0, v115
	v_pk_fma_f32 v[90:91], v[90:91], v[0:1], v[160:161] op_sel_hi:[1,0,1]
	v_pk_fma_f32 v[94:95], v[94:95], v[0:1], v[164:165] op_sel_hi:[1,0,1]
	v_pk_mul_f32 v[98:99], v[102:103], v[100:101]
	v_pk_mul_f32 v[94:95], v[90:91], v[94:95]
	v_cvt_pk_bf16_f32 v109, v98, v99
	v_add_co_u32_e32 v98, vcc, s0, v138
	s_nop 0
	v_permlane16_swap_b32_e32 v107, v109
	v_addc_co_u32_e32 v99, vcc, 0, v139, vcc
	global_store_dwordx4 v[98:99], v[106:109], off
	v_mul_f32_e32 v98, 0xbfb8aa3b, v90
	v_mul_f32_e32 v90, 0xbfb8aa3b, v91
	v_exp_f32_e32 v98, v98
	v_exp_f32_e32 v90, v90
	v_pk_fma_f32 v[92:93], v[92:93], v[0:1], v[162:163] op_sel_hi:[1,0,1]
	v_pk_fma_f32 v[96:97], v[96:97], v[0:1], v[166:167] op_sel_hi:[1,0,1]
	v_add_f32_e32 v98, 1.0, v98
	v_add_f32_e32 v90, 1.0, v90
	v_rcp_f32_e32 v98, v98
	v_rcp_f32_e32 v99, v90
	v_pk_mul_f32 v[96:97], v[92:93], v[96:97]
	v_pk_fma_f32 v[82:83], v[82:83], v[0:1], v[168:169] op_sel_hi:[1,0,1]
	v_pk_fma_f32 v[86:87], v[86:87], v[0:1], v[172:173] op_sel_hi:[1,0,1]
	v_pk_mul_f32 v[90:91], v[94:95], v[98:99]
	v_pk_mul_f32 v[86:87], v[82:83], v[86:87]
	v_cvt_pk_bf16_f32 v90, v90, v91
	v_mul_f32_e32 v91, 0xbfb8aa3b, v92
	v_exp_f32_e32 v91, v91
	s_mov_b32 s0, 0x42000
	v_add_f32_e32 v91, 1.0, v91
	v_rcp_f32_e32 v94, v91
	v_mul_f32_e32 v91, 0xbfb8aa3b, v93
	v_exp_f32_e32 v91, v91
	s_nop 0
	v_add_f32_e32 v91, 1.0, v91
	v_rcp_f32_e32 v95, v91
	s_nop 0
	v_pk_mul_f32 v[92:93], v[96:97], v[94:95]
	s_nop 0
	v_cvt_pk_bf16_f32 v91, v92, v93
	v_mul_f32_e32 v92, 0xbfb8aa3b, v82
	v_mul_f32_e32 v82, 0xbfb8aa3b, v83
	v_exp_f32_e32 v92, v92
	v_exp_f32_e32 v82, v82
	v_add_f32_e32 v92, 1.0, v92
	v_add_f32_e32 v82, 1.0, v82
	v_rcp_f32_e32 v92, v92
	v_rcp_f32_e32 v93, v82
	s_nop 0
	v_pk_mul_f32 v[82:83], v[86:87], v[92:93]
	s_nop 0
	v_cvt_pk_bf16_f32 v92, v82, v83
	v_pk_fma_f32 v[82:83], v[84:85], v[0:1], v[170:171] op_sel_hi:[1,0,1]
	v_pk_fma_f32 v[86:87], v[88:89], v[0:1], v[174:175] op_sel_hi:[1,0,1]
	v_mul_f32_e32 v84, 0xbfb8aa3b, v82
	v_mul_f32_e32 v0, 0xbfb8aa3b, v83
	v_exp_f32_e32 v84, v84
	v_exp_f32_e32 v0, v0
	v_pk_mul_f32 v[86:87], v[82:83], v[86:87]
	v_permlane16_swap_b32_e32 v90, v92
	v_add_f32_e32 v84, 1.0, v84
	v_add_f32_e32 v0, 1.0, v0
	v_rcp_f32_e32 v84, v84
	v_rcp_f32_e32 v85, v0
	s_nop 0
	v_pk_mul_f32 v[82:83], v[86:87], v[84:85]
	s_nop 0
	v_cvt_pk_bf16_f32 v93, v82, v83
	v_add_co_u32_e32 v82, vcc, s0, v138
	s_nop 0
	v_permlane16_swap_b32_e32 v91, v93
	v_addc_co_u32_e32 v83, vcc, 0, v139, vcc
	global_store_dwordx4 v[82:83], v[90:93], off
	ds_read2_b32 v[82:83], v144 offset0:128 offset1:144
	s_mov_b32 s0, 0xb0000
	s_waitcnt lgkmcnt(0)
; DI unsigned pk2(float a, float b) { f2_t v = {a, b}; bf2_t r = __builtin_convertvector(v, bf2_t); return __builtin_bit_cast(unsigned, r); }
; DI float silu_mul(float a, float b) { return a * b * __builtin_amdgcn_rcpf(1.f + __builtin_amdgcn_exp2f(a * -1.4426950408889634f)); }
;   DI void operator()(f32x4 (&acc)[2][2][4][2], int brow, int bcol, int wr, int wc, int fr, int fq, const int nai) const {
;     ...
;         const float r = rl[ai * 128 + wr * 64 + m * 16 + fr];
;         u16* o_ = ob + (size_t)(ai * 128 + m * 16) * DFF;
;         u32x2 p0, p1;
;         {
;           const f32x4 a = acc[ai][0][m][0], b = acc[ai][1][m][0];
;           p0[0] = pk2(silu_mul(a[0] * r + sa0.x, b[0] * r + sb0.x), silu_mul(a[1] * r + sa0.y, b[1] * r + sb0.y));
;           p0[1] = pk2(silu_mul(a[2] * r + sa0.z, b[2] * r + sb0.z), silu_mul(a[3] * r + sa0.w, b[3] * r + sb0.w));
;         }
;         {
;           const f32x4 a = acc[ai][0][m][1], b = acc[ai][1][m][1];
;           p1[0] = pk2(silu_mul(a[0] * r + sa1.x, b[0] * r + sb1.x), silu_mul(a[1] * r + sa1.y, b[1] * r + sb1.y));
;           p1[1] = pk2(silu_mul(a[2] * r + sa1.z, b[2] * r + sb1.z), silu_mul(a[3] * r + sa1.w, b[3] * r + sb1.w));
;         }
;         store_nn16(o_, p0, p1, fq);
;       }
	v_pk_fma_f32 v[74:75], v[74:75], v[82:83], v[160:161] op_sel_hi:[1,0,1]
	s_nop 0
	v_mul_f32_e32 v0, 0xbfb8aa3b, v74
	v_exp_f32_e32 v0, v0
	v_pk_fma_f32 v[76:77], v[76:77], v[82:83], v[162:163] op_sel_hi:[1,0,1]
	v_pk_fma_f32 v[78:79], v[78:79], v[82:83], v[164:165] op_sel_hi:[1,0,1]
	v_pk_fma_f32 v[66:67], v[66:67], v[82:83], v[168:169] op_sel_hi:[1,0,1]
	v_add_f32_e32 v0, 1.0, v0
	v_rcp_f32_e32 v84, v0
	v_mul_f32_e32 v0, 0xbfb8aa3b, v75
	v_exp_f32_e32 v0, v0
	v_pk_mul_f32 v[78:79], v[74:75], v[78:79]
	v_pk_fma_f32 v[80:81], v[80:81], v[82:83], v[166:167] op_sel_hi:[1,0,1]
	v_pk_fma_f32 v[70:71], v[70:71], v[82:83], v[172:173] op_sel_hi:[1,0,1]
	v_add_f32_e32 v0, 1.0, v0
	v_rcp_f32_e32 v85, v0
	v_mul_f32_e32 v0, 0xbfb8aa3b, v76
	v_exp_f32_e32 v0, v0
	v_pk_mul_f32 v[80:81], v[76:77], v[80:81]
	v_pk_mul_f32 v[74:75], v[78:79], v[84:85]
	v_pk_mul_f32 v[70:71], v[66:67], v[70:71]
	v_add_f32_e32 v0, 1.0, v0
	v_rcp_f32_e32 v78, v0
	v_mul_f32_e32 v0, 0xbfb8aa3b, v77
	v_exp_f32_e32 v0, v0
	v_cvt_pk_bf16_f32 v74, v74, v75
	v_add_f32_e32 v0, 1.0, v0
	v_rcp_f32_e32 v79, v0
	v_mul_f32_e32 v0, 0xbfb8aa3b, v66
	v_exp_f32_e32 v0, v0
	v_pk_mul_f32 v[76:77], v[80:81], v[78:79]
	s_nop 0
	v_cvt_pk_bf16_f32 v75, v76, v77
	v_add_f32_e32 v0, 1.0, v0
	v_rcp_f32_e32 v76, v0
	v_mul_f32_e32 v0, 0xbfb8aa3b, v67
	v_exp_f32_e32 v0, v0
	s_nop 0
	v_add_f32_e32 v0, 1.0, v0
	v_rcp_f32_e32 v77, v0
	s_nop 0
	v_pk_mul_f32 v[66:67], v[70:71], v[76:77]
	s_nop 0
	v_cvt_pk_bf16_f32 v76, v66, v67
	v_pk_fma_f32 v[66:67], v[68:69], v[82:83], v[170:171] op_sel_hi:[1,0,1]
	v_pk_fma_f32 v[70:71], v[72:73], v[82:83], v[174:175] op_sel_hi:[1,0,1]
	v_mul_f32_e32 v0, 0xbfb8aa3b, v66
	v_exp_f32_e32 v0, v0
	v_pk_mul_f32 v[70:71], v[66:67], v[70:71]
	v_permlane16_swap_b32_e32 v74, v76
	v_add_f32_e32 v0, 1.0, v0
	v_rcp_f32_e32 v68, v0
	v_mul_f32_e32 v0, 0xbfb8aa3b, v67
	v_exp_f32_e32 v0, v0
	s_nop 0
	v_add_f32_e32 v0, 1.0, v0
	v_rcp_f32_e32 v69, v0
	v_mov_b32_e32 v0, v83
	v_pk_fma_f32 v[58:59], v[58:59], v[0:1], v[160:161] op_sel_hi:[1,0,1]
	v_pk_fma_f32 v[62:63], v[62:63], v[0:1], v[164:165] op_sel_hi:[1,0,1]
	v_pk_mul_f32 v[66:67], v[70:71], v[68:69]
	v_pk_mul_f32 v[62:63], v[58:59], v[62:63]
	v_cvt_pk_bf16_f32 v77, v66, v67
	v_add_co_u32_e32 v66, vcc, s0, v138
	s_nop 0
	v_permlane16_swap_b32_e32 v75, v77
	v_addc_co_u32_e32 v67, vcc, 0, v139, vcc
	global_store_dwordx4 v[66:67], v[74:77], off
	v_mul_f32_e32 v66, 0xbfb8aa3b, v58
	v_mul_f32_e32 v58, 0xbfb8aa3b, v59
	v_exp_f32_e32 v66, v66
	v_exp_f32_e32 v58, v58
	v_pk_fma_f32 v[60:61], v[60:61], v[0:1], v[162:163] op_sel_hi:[1,0,1]
	v_pk_fma_f32 v[64:65], v[64:65], v[0:1], v[166:167] op_sel_hi:[1,0,1]
	v_add_f32_e32 v66, 1.0, v66
	v_add_f32_e32 v58, 1.0, v58
	v_rcp_f32_e32 v66, v66
	v_rcp_f32_e32 v67, v58
	v_pk_mul_f32 v[64:65], v[60:61], v[64:65]
	v_pk_fma_f32 v[50:51], v[50:51], v[0:1], v[168:169] op_sel_hi:[1,0,1]
	v_pk_fma_f32 v[54:55], v[54:55], v[0:1], v[172:173] op_sel_hi:[1,0,1]
	v_pk_mul_f32 v[58:59], v[62:63], v[66:67]
	v_pk_mul_f32 v[54:55], v[50:51], v[54:55]
	v_cvt_pk_bf16_f32 v58, v58, v59
	v_mul_f32_e32 v59, 0xbfb8aa3b, v60
	v_exp_f32_e32 v59, v59
	s_mov_b32 s0, 0xc6000
	v_add_f32_e32 v59, 1.0, v59
	v_rcp_f32_e32 v62, v59
	v_mul_f32_e32 v59, 0xbfb8aa3b, v61
	v_exp_f32_e32 v59, v59
	s_nop 0
	v_add_f32_e32 v59, 1.0, v59
	v_rcp_f32_e32 v63, v59
	s_nop 0
	v_pk_mul_f32 v[60:61], v[64:65], v[62:63]
	s_nop 0
	v_cvt_pk_bf16_f32 v59, v60, v61
	v_mul_f32_e32 v60, 0xbfb8aa3b, v50
	v_mul_f32_e32 v50, 0xbfb8aa3b, v51
	v_exp_f32_e32 v60, v60
	v_exp_f32_e32 v50, v50
	v_add_f32_e32 v60, 1.0, v60
	v_add_f32_e32 v50, 1.0, v50
	v_rcp_f32_e32 v60, v60
	v_rcp_f32_e32 v61, v50
	s_nop 0
	v_pk_mul_f32 v[50:51], v[54:55], v[60:61]
	s_nop 0
	v_cvt_pk_bf16_f32 v60, v50, v51
	v_pk_fma_f32 v[50:51], v[52:53], v[0:1], v[170:171] op_sel_hi:[1,0,1]
	v_pk_fma_f32 v[54:55], v[56:57], v[0:1], v[174:175] op_sel_hi:[1,0,1]
	v_mul_f32_e32 v52, 0xbfb8aa3b, v50
	v_mul_f32_e32 v0, 0xbfb8aa3b, v51
	v_exp_f32_e32 v52, v52
	v_exp_f32_e32 v0, v0
	v_pk_mul_f32 v[54:55], v[50:51], v[54:55]
	v_permlane16_swap_b32_e32 v58, v60
	v_add_f32_e32 v52, 1.0, v52
	v_add_f32_e32 v0, 1.0, v0
	v_rcp_f32_e32 v52, v52
	v_rcp_f32_e32 v53, v0
	s_nop 0
	v_pk_mul_f32 v[50:51], v[54:55], v[52:53]
	s_nop 0
	v_cvt_pk_bf16_f32 v61, v50, v51
	v_add_co_u32_e32 v50, vcc, s0, v138
	s_nop 0
	v_permlane16_swap_b32_e32 v59, v61
	v_addc_co_u32_e32 v51, vcc, 0, v139, vcc
	global_store_dwordx4 v[50:51], v[58:61], off
	ds_read2_b32 v[50:51], v144 offset0:160 offset1:176
	s_mov_b32 s0, 0xdc000
	s_waitcnt lgkmcnt(0)
; DI unsigned pk2(float a, float b) { f2_t v = {a, b}; bf2_t r = __builtin_convertvector(v, bf2_t); return __builtin_bit_cast(unsigned, r); }
; #define WAIT_V(n) asm volatile("s_waitcnt vmcnt(" #n ")" ::: "memory")
; DI float silu_mul(float a, float b) { return a * b * __builtin_amdgcn_rcpf(1.f + __builtin_amdgcn_exp2f(a * -1.4426950408889634f)); }
; template <int K, bool HALFM, class Epi>
; DI void gemm_tile(unsigned char* lds, const int tid, const u16* __restrict__ A, const u16* __restrict__ Bt, int brow, int bcol, Epi& epi,
;                   const bool prefetched, const bool has_next, const int nbrow, const int nbcol) {
;     ...
;   WAIT_V(0);
;   DI void operator()(f32x4 (&acc)[2][2][4][2], int brow, int bcol, int wr, int wc, int fr, int fq, const int nai) const {
;     ...
;         const float r = rl[ai * 128 + wr * 64 + m * 16 + fr];
;         u16* o_ = ob + (size_t)(ai * 128 + m * 16) * DFF;
;         u32x2 p0, p1;
;         {
;           const f32x4 a = acc[ai][0][m][0], b = acc[ai][1][m][0];
;           p0[0] = pk2(silu_mul(a[0] * r + sa0.x, b[0] * r + sb0.x), silu_mul(a[1] * r + sa0.y, b[1] * r + sb0.y));
;           p0[1] = pk2(silu_mul(a[2] * r + sa0.z, b[2] * r + sb0.z), silu_mul(a[3] * r + sa0.w, b[3] * r + sb0.w));
;         }
;         {
;           const f32x4 a = acc[ai][0][m][1], b = acc[ai][1][m][1];
;           p1[0] = pk2(silu_mul(a[0] * r + sa1.x, b[0] * r + sb1.x), silu_mul(a[1] * r + sa1.y, b[1] * r + sb1.y));
;           p1[1] = pk2(silu_mul(a[2] * r + sa1.z, b[2] * r + sb1.z), silu_mul(a[3] * r + sa1.w, b[3] * r + sb1.w));
;         }
;         store_nn16(o_, p0, p1, fq);
;       }
	v_pk_fma_f32 v[26:27], v[26:27], v[50:51], v[160:161] op_sel_hi:[1,0,1]
	s_nop 0
	v_mul_f32_e32 v0, 0xbfb8aa3b, v26
	v_exp_f32_e32 v0, v0
	v_pk_fma_f32 v[28:29], v[28:29], v[50:51], v[162:163] op_sel_hi:[1,0,1]
	v_pk_fma_f32 v[38:39], v[38:39], v[50:51], v[164:165] op_sel_hi:[1,0,1]
	v_pk_fma_f32 v[18:19], v[18:19], v[50:51], v[168:169] op_sel_hi:[1,0,1]
	v_add_f32_e32 v0, 1.0, v0
	v_rcp_f32_e32 v52, v0
	v_mul_f32_e32 v0, 0xbfb8aa3b, v27
	v_exp_f32_e32 v0, v0
	v_pk_mul_f32 v[38:39], v[26:27], v[38:39]
	v_pk_fma_f32 v[40:41], v[40:41], v[50:51], v[166:167] op_sel_hi:[1,0,1]
	v_pk_fma_f32 v[22:23], v[22:23], v[50:51], v[172:173] op_sel_hi:[1,0,1]
	v_add_f32_e32 v0, 1.0, v0
	v_rcp_f32_e32 v53, v0
	v_mul_f32_e32 v0, 0xbfb8aa3b, v28
	v_exp_f32_e32 v0, v0
	v_pk_mul_f32 v[40:41], v[28:29], v[40:41]
	v_pk_mul_f32 v[26:27], v[38:39], v[52:53]
	v_pk_mul_f32 v[22:23], v[18:19], v[22:23]
	v_add_f32_e32 v0, 1.0, v0
	v_rcp_f32_e32 v38, v0
	v_mul_f32_e32 v0, 0xbfb8aa3b, v29
	v_exp_f32_e32 v0, v0
	v_cvt_pk_bf16_f32 v26, v26, v27
	v_add_f32_e32 v0, 1.0, v0
	v_rcp_f32_e32 v39, v0
	v_mul_f32_e32 v0, 0xbfb8aa3b, v18
	v_exp_f32_e32 v0, v0
	v_pk_mul_f32 v[28:29], v[40:41], v[38:39]
	s_nop 0
	v_cvt_pk_bf16_f32 v27, v28, v29
	v_add_f32_e32 v0, 1.0, v0
	v_rcp_f32_e32 v28, v0
	v_mul_f32_e32 v0, 0xbfb8aa3b, v19
	v_exp_f32_e32 v0, v0
	s_nop 0
	v_add_f32_e32 v0, 1.0, v0
	v_rcp_f32_e32 v29, v0
	s_nop 0
	v_pk_mul_f32 v[18:19], v[22:23], v[28:29]
	s_nop 0
	v_cvt_pk_bf16_f32 v28, v18, v19
	v_pk_fma_f32 v[18:19], v[20:21], v[50:51], v[170:171] op_sel_hi:[1,0,1]
	v_pk_fma_f32 v[22:23], v[24:25], v[50:51], v[174:175] op_sel_hi:[1,0,1]
	v_mul_f32_e32 v0, 0xbfb8aa3b, v18
	v_exp_f32_e32 v0, v0
	v_pk_mul_f32 v[22:23], v[18:19], v[22:23]
	v_permlane16_swap_b32_e32 v26, v28
	v_add_f32_e32 v0, 1.0, v0
	v_rcp_f32_e32 v20, v0
	v_mul_f32_e32 v0, 0xbfb8aa3b, v19
	v_exp_f32_e32 v0, v0
	s_nop 0
	v_add_f32_e32 v0, 1.0, v0
	v_rcp_f32_e32 v21, v0
	v_mov_b32_e32 v0, v51
	v_pk_fma_f32 v[10:11], v[10:11], v[0:1], v[160:161] op_sel_hi:[1,0,1]
	v_pk_fma_f32 v[14:15], v[14:15], v[0:1], v[164:165] op_sel_hi:[1,0,1]
	v_pk_mul_f32 v[18:19], v[22:23], v[20:21]
	v_pk_mul_f32 v[14:15], v[10:11], v[14:15]
	v_cvt_pk_bf16_f32 v29, v18, v19
	v_add_co_u32_e32 v18, vcc, s0, v138
	s_nop 0
	v_permlane16_swap_b32_e32 v27, v29
	v_addc_co_u32_e32 v19, vcc, 0, v139, vcc
	global_store_dwordx4 v[18:19], v[26:29], off
	v_mul_f32_e32 v18, 0xbfb8aa3b, v10
	v_mul_f32_e32 v10, 0xbfb8aa3b, v11
	v_exp_f32_e32 v18, v18
	v_exp_f32_e32 v10, v10
	v_pk_fma_f32 v[12:13], v[12:13], v[0:1], v[162:163] op_sel_hi:[1,0,1]
	v_pk_fma_f32 v[16:17], v[16:17], v[0:1], v[166:167] op_sel_hi:[1,0,1]
	v_add_f32_e32 v18, 1.0, v18
	v_add_f32_e32 v10, 1.0, v10
	v_rcp_f32_e32 v18, v18
	v_rcp_f32_e32 v19, v10
	v_pk_mul_f32 v[16:17], v[12:13], v[16:17]
	v_pk_fma_f32 v[2:3], v[2:3], v[0:1], v[168:169] op_sel_hi:[1,0,1]
	v_pk_fma_f32 v[6:7], v[6:7], v[0:1], v[172:173] op_sel_hi:[1,0,1]
	v_pk_mul_f32 v[10:11], v[14:15], v[18:19]
	v_pk_mul_f32 v[6:7], v[2:3], v[6:7]
	v_cvt_pk_bf16_f32 v10, v10, v11
	v_mul_f32_e32 v11, 0xbfb8aa3b, v12
	v_exp_f32_e32 v11, v11
	s_nop 0
	v_add_f32_e32 v11, 1.0, v11
	v_rcp_f32_e32 v14, v11
	v_mul_f32_e32 v11, 0xbfb8aa3b, v13
	v_exp_f32_e32 v11, v11
	s_nop 0
	v_add_f32_e32 v11, 1.0, v11
	v_rcp_f32_e32 v15, v11
	s_nop 0
	v_pk_mul_f32 v[12:13], v[16:17], v[14:15]
	s_nop 0
	v_cvt_pk_bf16_f32 v11, v12, v13
	v_mul_f32_e32 v12, 0xbfb8aa3b, v2
	v_mul_f32_e32 v2, 0xbfb8aa3b, v3
	v_exp_f32_e32 v12, v12
	v_exp_f32_e32 v2, v2
	v_add_f32_e32 v12, 1.0, v12
	v_add_f32_e32 v2, 1.0, v2
	v_rcp_f32_e32 v12, v12
	v_rcp_f32_e32 v13, v2
	s_nop 0
	v_pk_mul_f32 v[2:3], v[6:7], v[12:13]
	s_nop 0
	v_cvt_pk_bf16_f32 v12, v2, v3
	v_pk_fma_f32 v[2:3], v[4:5], v[0:1], v[170:171] op_sel_hi:[1,0,1]
	v_pk_fma_f32 v[6:7], v[8:9], v[0:1], v[174:175] op_sel_hi:[1,0,1]
	v_mul_f32_e32 v4, 0xbfb8aa3b, v2
	v_mul_f32_e32 v0, 0xbfb8aa3b, v3
	v_exp_f32_e32 v4, v4
	v_exp_f32_e32 v0, v0
	v_pk_mul_f32 v[6:7], v[2:3], v[6:7]
	v_permlane16_swap_b32_e32 v10, v12
	v_add_f32_e32 v4, 1.0, v4
	v_add_f32_e32 v0, 1.0, v0
	v_rcp_f32_e32 v4, v4
	v_rcp_f32_e32 v5, v0
	s_nop 0
	v_pk_mul_f32 v[2:3], v[6:7], v[4:5]
	s_nop 0
	v_cvt_pk_bf16_f32 v13, v2, v3
	v_add_co_u32_e32 v2, vcc, 0xf2000, v138
	s_nop 0
	v_permlane16_swap_b32_e32 v11, v13
	v_addc_co_u32_e32 v3, vcc, 0, v139, vcc
	global_store_dwordx4 v[2:3], v[10:13], off
	s_waitcnt vmcnt(0)

; template <int K, bool HALFM, class Epi>
; DI void gemm_tile(unsigned char* lds, const int tid, const u16* __restrict__ A, const u16* __restrict__ Bt, int brow, int bcol, Epi& epi,
;                   const bool prefetched, const bool has_next, const int nbrow, const int nbcol) {
;     ...
;   if (has_next) {
;     STAGE(SB(0, 0), Bt, nbcol, 0); STAGE(SA(0, 0), A, nbrow, 0);
;     STAGE(SB(0, 1), Bt, nbcol + HALF, 0); STAGE(SA(0, 1), A, nbrow + AH, 0);
;     STAGE(SB(1, 0), Bt, nbcol, 1); STAGE(SA(1, 0), A, nbrow, 1); STAGE(SB(1, 1), Bt, nbcol + HALF, 1);
;   }
;   DI void operator()(f32x4 (&acc)[2][2][4][2], int brow, int bcol, int wr, int wc, int fr, int fq, const int nai) const {
;     ...
;     const float* swr = sw + bi * SW_LD + bcol + wc * 32 + fq * 4;
;     const float4 sa0 = ld4(swr), sa1 = ld4(swr + 16), sb0 = ld4(swr + 128), sb1 = ld4(swr + 144);
.LBB0_999:
	s_or_b64 exec, exec, s[0:1]
	s_min_i32 s100, s2, 0x4000
	s_ashr_i32 s100, s100, 11
	s_mul_hi_i32 s101, s100, 0x5800
	s_mulk_i32 s100, 0x5800
	s_add_u32 s100, s16, s100
	s_addc_u32 s101, s17, s101
	s_lshl_b64 vcc, s[8:9], 2
	s_add_u32 s100, s100, vcc_lo
	s_addc_u32 s101, s101, vcc_hi
	v_lshrrev_b32_e32 v152, 1, v138
	v_and_b32_e32 v152, 0x60, v152
	v_lshlrev_b32_e32 v152, 2, v152
	v_and_b32_e32 v153, 48, v138
	v_add_u32_e32 v152, v152, v153
	global_load_dwordx4 v[160:163], v152, s[100:101]
	global_load_dwordx4 v[164:167], v152, s[100:101] offset:512
	global_load_dwordx4 v[168:171], v152, s[100:101] offset:64
	global_load_dwordx4 v[172:175], v152, s[100:101] offset:576
	s_andn2_b64 vcc, exec, s[46:47]
	s_mov_b32 s54, 0x800000
	s_movk_i32 s62, 0x21ff
	s_movk_i32 s63, 0x2000
	s_cbranch_vccnz .Lsw_nonext
	s_ashr_i32 s7, s6, 31
	s_lshl_b64 s[0:1], s[6:7], 11
	s_add_u32 s0, s18, s0
	s_addc_u32 s1, s19, s1
	s_mov_b32 m0, s5
	s_nop 0
	global_load_lds_dwordx4 v139, s[0:1]
	s_mov_b32 m0, s53
	s_nop 0
	global_load_lds_dwordx4 v0, s[0:1]
	s_ashr_i32 s5, s4, 31
	s_lshl_b64 s[10:11], s[4:5], 11
	v_readlane_b32 s12, v254, 59
	v_readlane_b32 s13, v254, 60
	s_add_u32 s10, s12, s10
	s_addc_u32 s11, s13, s11
	s_bitset1_b32 s6, 7
	s_ashr_i32 s7, s6, 31
	s_lshl_b64 s[6:7], s[6:7], 11
	s_add_u32 s6, s18, s6
	s_addc_u32 s7, s19, s7
	s_bitset1_b32 s4, 7
	s_ashr_i32 s5, s4, 31
	s_lshl_b64 s[4:5], s[4:5], 11
	s_add_u32 s4, s12, s4
	s_mov_b32 m0, s21
	s_nop 0
	global_load_lds_dwordx4 v139, s[10:11]
	s_mov_b32 m0, s52
	s_nop 0
	global_load_lds_dwordx4 v0, s[10:11]
	s_addc_u32 s5, s13, s5
	s_mov_b32 m0, s15
	s_nop 0
	global_load_lds_dwordx4 v139, s[6:7]
	s_mov_b32 m0, s51
	s_nop 0
	global_load_lds_dwordx4 v0, s[6:7]
	s_add_u32 s0, s0, 0x80
	s_mov_b32 m0, s3
	s_nop 0
	global_load_lds_dwordx4 v139, s[4:5]
	s_mov_b32 m0, s14
	s_nop 0
	global_load_lds_dwordx4 v0, s[4:5]
	s_addc_u32 s1, s1, 0
	s_mov_b32 m0, s31
	s_nop 0
	global_load_lds_dwordx4 v139, s[0:1]
	s_mov_b32 m0, s34
	s_nop 0
	global_load_lds_dwordx4 v0, s[0:1]
	s_add_u32 s0, s10, 0x80
	s_addc_u32 s1, s11, 0
	s_mov_b32 m0, s35
	s_nop 0
	global_load_lds_dwordx4 v139, s[0:1]
	s_mov_b32 m0, s48
	s_nop 0
	global_load_lds_dwordx4 v0, s[0:1]
	s_add_u32 s0, s6, 0x80
	s_addc_u32 s1, s7, 0
	s_mov_b32 m0, s49
	s_nop 0
	global_load_lds_dwordx4 v139, s[0:1]
	s_mov_b32 m0, s50
	s_nop 0
	global_load_lds_dwordx4 v0, s[0:1]
	s_waitcnt vmcnt(14)
	s_branch .LBB0_969
.Lsw_nonext:
	s_waitcnt vmcnt(0)
	s_branch .LBB0_969
